# phase 4 roles: wave 4 is the only scan-feed loader (priority 3), wave 5 is a third attention wave from the start (K/V tile in an 18 KB static LDS extension)
# speedup vs baseline: 1.0869x; 1.0113x over previous
.LBB0_452:
	s_and_b64 vcc, exec, s[0:1]
	s_cbranch_vccz .LBB0_552
	v_readfirstlane_b32 s12, v166
	v_cmp_gt_i32_e32 vcc, 12, v166
	s_waitcnt vmcnt(0) lgkmcnt(0)
	s_barrier
	s_and_saveexec_b64 s[0:1], vcc
	v_lshl_add_u32 v0, v166, 2, 0
	v_add_u32_e32 v0, 0x15000, v0
	ds_write_b32 v0, v1
	s_or_b64 exec, exec, s[0:1]
	s_ashr_i32 s82, s12, 6
	s_cmp_lt_i32 s82, 4
	s_cselect_b64 s[0:1], -1, 0
	s_cmp_gt_i32 s82, 4
	s_waitcnt lgkmcnt(0)
	s_barrier
	s_cbranch_scc1 .LBB0_457
	s_setprio 3
.LBB0_457:
	s_cmp_gt_i32 s82, 4
	v_and_b32_e32 v161, 63, v166
	s_cbranch_scc1 .LBB0_519
	v_writelane_b32 v255, s0, 39
	s_mov_b32 s96, s88
	s_nop 0
	v_writelane_b32 v255, s1, 40
	v_readlane_b32 s0, v250, 34
	v_readlane_b32 s1, v250, 35
	s_andn2_b64 vcc, exec, s[0:1]
	s_cbranch_vccnz .LBB0_512
	v_lshlrev_b32_e32 v0, 4, v161
	v_readlane_b32 s0, v255, 35
	v_and_b32_e32 v170, 0xf0, v0
	v_mov_b32_e32 v171, v1
	v_readlane_b32 s1, v255, 36
	v_and_b32_e32 v0, 0x1f0, v0
	v_and_b32_e32 v2, 1, v166
	v_lshl_add_u64 v[172:173], s[0:1], 0, v[170:171]
	v_readlane_b32 s0, v255, 33
	v_readlane_b32 s1, v255, 34
	v_lshlrev_b32_e32 v187, 5, v2
	v_lshrrev_b32_e32 v191, 5, v161
	v_lshl_add_u64 v[174:175], s[0:1], 0, v[0:1]
	v_lshlrev_b32_e32 v0, 3, v2
	v_or_b32_e32 v2, 64, v161
	v_lshrrev_b32_e32 v188, 4, v2
	v_lshrrev_b32_e32 v192, 5, v2
	s_movk_i32 s0, 0x500
	v_mov_b32_e32 v2, 0x2800
	v_mad_u32_u24 v229, v191, s0, v2
	v_mov_b32_e32 v2, 0x3200
	v_lshlrev_b32_e32 v3, 5, v161
	v_mad_u32_u24 v230, v191, s0, v2
	v_mov_b32_e32 v2, 0x3c00
	v_lshrrev_b32_e32 v167, 4, v161
	v_and_b32_e32 v185, 0x3e0, v3
	v_and_b32_e32 v186, 0x3c0, v3
	v_or_b32_e32 v3, 0x80, v161
	v_or_b32_e32 v4, 0xc0, v161
	v_mad_u32_u24 v231, v191, s0, v2
	v_mov_b32_e32 v2, 0x4600
	s_cmp_lt_i32 s82, 4
	v_lshl_or_b32 v169, s82, 2, v167
	v_and_b32_e32 v182, 15, v166
	v_lshrrev_b32_e32 v189, 4, v3
	v_lshrrev_b32_e32 v190, 4, v4
	v_lshrrev_b32_e32 v193, 5, v3
	v_lshrrev_b32_e32 v194, 5, v4
	v_mad_u32_u24 v232, v191, s0, v2
	v_readlane_b32 s0, v255, 13
	s_cselect_b64 s[42:43], -1, 0
	v_lshlrev_b32_e32 v168, 2, v182
	v_lshlrev_b32_e32 v183, 4, v182
	v_lshlrev_b32_e32 v184, 2, v169
	s_mov_b32 s83, 0
	v_cmp_eq_u32_e64 s[38:39], 0, v161
	v_bfe_u32 v171, v166, 1, 4
	v_cmp_gt_u32_e64 s[44:45], 32, v161
	v_cmp_eq_u32_e64 s[8:9], 0, v182
	v_cmp_eq_u32_e64 s[10:11], 1, v182
	v_cmp_eq_u32_e64 s[18:19], 2, v182
	v_cmp_eq_u32_e64 s[6:7], 3, v182
	v_cmp_eq_u32_e64 s[80:81], 4, v182
	v_cmp_eq_u32_e64 s[90:91], 5, v182
	v_cmp_eq_u32_e64 s[74:75], 6, v182
	v_cmp_eq_u32_e64 s[56:57], 7, v182
	v_cmp_eq_u32_e64 s[58:59], 8, v182
	v_cmp_eq_u32_e64 s[60:61], 9, v182
	v_cmp_eq_u32_e64 s[62:63], 10, v182
	v_cmp_eq_u32_e64 s[64:65], 11, v182
	v_cmp_eq_u32_e64 s[66:67], 12, v182
	v_cmp_eq_u32_e64 s[68:69], 14, v182
	v_cmp_eq_u32_e64 s[70:71], 13, v182
	v_cmp_eq_u32_e64 s[72:73], 15, v182
	v_or_b32_e32 v195, 8, v191
	v_or_b32_e32 v196, 10, v191
	v_or_b32_e32 v197, 12, v191
	v_or_b32_e32 v198, 14, v191
	v_mul_u32_u24_e32 v199, 0x500, v167
	v_mul_u32_u24_e32 v200, 0x500, v188
	v_mul_u32_u24_e32 v201, 0x500, v189
	v_mul_u32_u24_e32 v224, 0x500, v190
	v_mul_u32_u24_e32 v225, 0x500, v191
	v_mul_u32_u24_e32 v226, 0x500, v192
	v_mul_u32_u24_e32 v227, 0x500, v193
	v_mul_u32_u24_e32 v228, 0x500, v194
	v_lshlrev_b32_e32 v0, 1, v0
	s_and_b32 s84, s0, 7
	s_lshl_b32 s84, s84, 5
	s_lshr_b32 s1, s0, 3
	s_add_i32 s84, s84, s1
	v_readlane_b32 s1, v255, 14
	s_branch .LBB0_462

.LBB0_478:
	s_and_b64 vcc, exec, s[12:13]
	s_cbranch_vccz .LBB0_460
	s_add_i32 s0, s83, s82
	s_mov_b32 s77, 0
	s_cmp_eq_u32 s85, s77
	v_readlane_b32 s96, v255, 15
	v_readlane_b32 s97, v255, 16
	s_cbranch_scc1 .LBB0_461
	s_sub_i32 s0, s85, s77
	s_add_i32 s1, s0, 1
	s_mov_b32 s12, s85
	s_lshl_b32 s1, s77, 4
	s_lshl_b32 s36, s89, 8
	s_add_i32 s86, s12, -1
	s_add_i32 s13, s87, s1
	v_lshl_add_u64 v[176:177], v[172:173], 0, s[36:37]
	s_lshl_b32 s36, s89, 9
	s_mov_b32 s1, s86
	s_cmp_lt_u32 s0, 2
	s_cselect_b32 s0, s1, 1
	s_or_b32 s0, s0, s77
	s_lshl_b32 s0, s0, 4
	s_add_i32 s78, s0, s87
	s_waitcnt vmcnt(7)
	v_add_u32_e32 v54, s78, v171
	v_ashrrev_i32_e32 v55, 31, v54
	v_readlane_b32 s40, v255, 19
	v_lshlrev_b64 v[54:55], 11, v[54:55]
	v_readlane_b32 s41, v255, 20
	v_lshl_add_u64 v[178:179], v[174:175], 0, s[36:37]
	s_lshl_b32 s36, s89, 7
	v_lshl_add_u64 v[54:55], s[40:41], 0, v[54:55]
	v_add_u32_e32 v56, s78, v198
	v_lshl_add_u64 v[54:55], v[54:55], 0, s[36:37]
	s_lshl_b32 s0, s88, 5
	s_mov_b32 s1, s37
	v_ashrrev_i32_e32 v57, 31, v56
	v_lshl_add_u64 v[54:55], v[54:55], 0, s[0:1]
	v_lshlrev_b64 v[56:57], 13, v[56:57]
	v_lshl_add_u64 v[54:55], v[54:55], 0, v[0:1]
	v_lshl_add_u64 v[56:57], v[178:179], 0, v[56:57]
	global_load_dwordx4 v[78:81], v[54:55], off
	global_load_dwordx4 v[66:69], v[56:57], off
	v_add_u32_e32 v54, s78, v197
	v_add_u32_e32 v56, s78, v196
	v_ashrrev_i32_e32 v55, 31, v54
	v_ashrrev_i32_e32 v57, 31, v56
	v_lshlrev_b64 v[54:55], 13, v[54:55]
	v_lshlrev_b64 v[56:57], 13, v[56:57]
	v_lshl_add_u64 v[54:55], v[178:179], 0, v[54:55]
	v_lshl_add_u64 v[56:57], v[178:179], 0, v[56:57]
	global_load_dwordx4 v[94:97], v[54:55], off
	global_load_dwordx4 v[62:65], v[56:57], off
	v_add_u32_e32 v54, s78, v195
	v_add_u32_e32 v56, s78, v194
	v_ashrrev_i32_e32 v55, 31, v54
	v_ashrrev_i32_e32 v57, 31, v56
	v_lshlrev_b64 v[54:55], 13, v[54:55]
	v_lshlrev_b64 v[56:57], 13, v[56:57]
	v_lshl_add_u64 v[54:55], v[178:179], 0, v[54:55]
	v_lshl_add_u64 v[56:57], v[178:179], 0, v[56:57]
	global_load_dwordx4 v[90:93], v[54:55], off
	global_load_dwordx4 v[58:61], v[56:57], off
	v_add_u32_e32 v54, s78, v193
	v_add_u32_e32 v56, s78, v192
	v_add_u32_e32 v70, s78, v191
	v_add_u32_e32 v72, s78, v190
	v_ashrrev_i32_e32 v55, 31, v54
	v_ashrrev_i32_e32 v57, 31, v56
	v_ashrrev_i32_e32 v71, 31, v70
	v_ashrrev_i32_e32 v73, 31, v72
	v_add_u32_e32 v104, s13, v171
	v_lshlrev_b64 v[54:55], 13, v[54:55]
	v_lshlrev_b64 v[56:57], 13, v[56:57]
	v_lshlrev_b64 v[70:71], 13, v[70:71]
	v_lshlrev_b64 v[72:73], 12, v[72:73]
	v_ashrrev_i32_e32 v105, 31, v104
	v_lshl_add_u64 v[54:55], v[178:179], 0, v[54:55]
	v_lshl_add_u64 v[56:57], v[178:179], 0, v[56:57]
	v_lshl_add_u64 v[70:71], v[178:179], 0, v[70:71]
	v_lshl_add_u64 v[72:73], v[176:177], 0, v[72:73]
	v_lshlrev_b64 v[104:105], 11, v[104:105]
	global_load_dwordx4 v[86:89], v[54:55], off
	s_nop 0
	global_load_dwordx4 v[54:57], v[56:57], off
	s_nop 0
	global_load_dwordx4 v[82:85], v[70:71], off
	global_load_dwordx4 v[74:77], v[72:73], off
	v_add_u32_e32 v70, s78, v189
	v_add_u32_e32 v72, s78, v188
	v_add_u32_e32 v102, s78, v167
	v_lshl_add_u64 v[104:105], s[40:41], 0, v[104:105]
	s_waitcnt vmcnt(14)
	v_add_u32_e32 v110, s13, v198
	v_add_u32_e32 v112, s13, v197
	v_ashrrev_i32_e32 v71, 31, v70
	v_ashrrev_i32_e32 v73, 31, v72
	v_ashrrev_i32_e32 v103, 31, v102
	v_lshl_add_u64 v[104:105], v[104:105], 0, s[36:37]
	v_ashrrev_i32_e32 v111, 31, v110
	v_ashrrev_i32_e32 v113, 31, v112
	v_lshlrev_b64 v[70:71], 12, v[70:71]
	v_lshlrev_b64 v[72:73], 12, v[72:73]
	v_lshlrev_b64 v[102:103], 12, v[102:103]
	v_lshl_add_u64 v[104:105], v[104:105], 0, s[0:1]
	v_lshlrev_b64 v[110:111], 13, v[110:111]
	v_lshlrev_b64 v[112:113], 13, v[112:113]
	v_lshl_add_u64 v[70:71], v[176:177], 0, v[70:71]
	v_lshl_add_u64 v[72:73], v[176:177], 0, v[72:73]
	v_lshl_add_u64 v[102:103], v[176:177], 0, v[102:103]
	s_waitcnt vmcnt(10)
	v_lshl_add_u64 v[106:107], v[104:105], 0, v[0:1]
	v_lshl_add_u64 v[110:111], v[178:179], 0, v[110:111]
	v_lshl_add_u64 v[112:113], v[178:179], 0, v[112:113]
	global_load_dwordx4 v[98:101], v[70:71], off
	s_nop 0
	global_load_dwordx4 v[70:73], v[72:73], off
	s_nop 0
	global_load_dwordx4 v[102:105], v[102:103], off
	s_nop 0
	global_load_dwordx4 v[106:109], v[106:107], off
	s_nop 0
	global_load_dwordx4 v[138:141], v[110:111], off
	global_load_dwordx4 v[134:137], v[112:113], off
	v_add_u32_e32 v110, s13, v196
	v_add_u32_e32 v112, s13, v195
	v_ashrrev_i32_e32 v111, 31, v110
	v_ashrrev_i32_e32 v113, 31, v112
	v_lshlrev_b64 v[110:111], 13, v[110:111]
	v_lshlrev_b64 v[112:113], 13, v[112:113]
	v_lshl_add_u64 v[110:111], v[178:179], 0, v[110:111]
	v_lshl_add_u64 v[112:113], v[178:179], 0, v[112:113]
	global_load_dwordx4 v[130:133], v[110:111], off
	global_load_dwordx4 v[126:129], v[112:113], off
	v_add_u32_e32 v110, s13, v194
	v_add_u32_e32 v112, s13, v193
	v_ashrrev_i32_e32 v111, 31, v110
	v_ashrrev_i32_e32 v113, 31, v112
	v_lshlrev_b64 v[110:111], 13, v[110:111]
	v_lshlrev_b64 v[112:113], 13, v[112:113]
	v_lshl_add_u64 v[110:111], v[178:179], 0, v[110:111]
	v_lshl_add_u64 v[112:113], v[178:179], 0, v[112:113]
	global_load_dwordx4 v[122:125], v[110:111], off
	global_load_dwordx4 v[118:121], v[112:113], off
	v_add_u32_e32 v110, s13, v192
	v_add_u32_e32 v112, s13, v191
	v_add_u32_e32 v142, s13, v190
	v_add_u32_e32 v144, s13, v189
	v_ashrrev_i32_e32 v111, 31, v110
	v_ashrrev_i32_e32 v113, 31, v112
	v_ashrrev_i32_e32 v143, 31, v142
	v_ashrrev_i32_e32 v145, 31, v144
	v_lshlrev_b64 v[110:111], 13, v[110:111]
	v_lshlrev_b64 v[112:113], 13, v[112:113]
	v_lshlrev_b64 v[142:143], 12, v[142:143]
	v_lshlrev_b64 v[144:145], 12, v[144:145]
	v_lshl_add_u64 v[110:111], v[178:179], 0, v[110:111]
	v_lshl_add_u64 v[112:113], v[178:179], 0, v[112:113]
	v_lshl_add_u64 v[142:143], v[176:177], 0, v[142:143]
	v_lshl_add_u64 v[144:145], v[176:177], 0, v[144:145]
	global_load_dwordx4 v[114:117], v[110:111], off
	s_nop 0
	global_load_dwordx4 v[110:113], v[112:113], off
	s_nop 0
	global_load_dwordx4 v[154:157], v[142:143], off
	global_load_dwordx4 v[150:153], v[144:145], off
	v_add_u32_e32 v142, s13, v188
	v_add_u32_e32 v144, s13, v167
	v_ashrrev_i32_e32 v143, 31, v142
	v_ashrrev_i32_e32 v145, 31, v144
	v_lshlrev_b64 v[142:143], 12, v[142:143]
	v_lshlrev_b64 v[144:145], 12, v[144:145]
	v_lshl_add_u64 v[142:143], v[176:177], 0, v[142:143]
	v_lshl_add_u64 v[144:145], v[176:177], 0, v[144:145]
	global_load_dwordx4 v[146:149], v[142:143], off
	s_nop 0
	global_load_dwordx4 v[142:145], v[144:145], off
	s_add_u32 s1, s40, s36
	s_addc_u32 s36, s41, 0
	s_add_u32 s0, s1, s0
	s_addc_u32 s1, s36, 0
	v_lshl_add_u64 v[180:181], s[0:1], 0, v[0:1]
	s_add_i32 s36, s77, s83
	s_mov_b32 s87, 0
	s_branch .LBB0_483

.LBB0_483:
	s_cmp_ge_u32 s87, s12
	s_cbranch_scc1 .LBB0_494
	s_add_i32 s0, s87, 2
	s_cmp_lt_u32 s0, s12
	s_cselect_b32 s0, s0, s86
	s_lshl_b32 s0, s0, 4
	s_add_i32 s0, s0, s13
	s_waitcnt vmcnt(12)
	v_add_u32_e32 v2, s0, v167
	v_add_u32_e32 v4, s0, v188
	s_waitcnt vmcnt(10)
	v_add_u32_e32 v10, s0, v189
	v_add_u32_e32 v12, s0, v190
	s_waitcnt vmcnt(8)
	v_add_u32_e32 v18, s0, v191
	v_add_u32_e32 v20, s0, v192
	s_waitcnt vmcnt(6)
	v_add_u32_e32 v26, s0, v193
	v_add_u32_e32 v28, s0, v194
	s_waitcnt vmcnt(4)
	v_add_u32_e32 v34, s0, v195
	v_add_u32_e32 v36, s0, v196
	s_waitcnt vmcnt(2)
	v_add_u32_e32 v42, s0, v197
	v_add_u32_e32 v44, s0, v198
	s_waitcnt vmcnt(0)
	v_add_u32_e32 v50, s0, v171
	v_ashrrev_i32_e32 v3, 31, v2
	v_ashrrev_i32_e32 v5, 31, v4
	v_ashrrev_i32_e32 v11, 31, v10
	v_ashrrev_i32_e32 v13, 31, v12
	v_ashrrev_i32_e32 v19, 31, v18
	v_ashrrev_i32_e32 v21, 31, v20
	v_ashrrev_i32_e32 v27, 31, v26
	v_ashrrev_i32_e32 v29, 31, v28
	v_ashrrev_i32_e32 v35, 31, v34
	v_ashrrev_i32_e32 v37, 31, v36
	v_ashrrev_i32_e32 v43, 31, v42
	v_ashrrev_i32_e32 v45, 31, v44
	v_ashrrev_i32_e32 v51, 31, v50
	v_lshlrev_b64 v[2:3], 12, v[2:3]
	v_lshlrev_b64 v[4:5], 12, v[4:5]
	v_lshlrev_b64 v[10:11], 12, v[10:11]
	v_lshlrev_b64 v[12:13], 12, v[12:13]
	v_lshlrev_b64 v[18:19], 13, v[18:19]
	v_lshlrev_b64 v[20:21], 13, v[20:21]
	v_lshlrev_b64 v[26:27], 13, v[26:27]
	v_lshlrev_b64 v[28:29], 13, v[28:29]
	v_lshlrev_b64 v[34:35], 13, v[34:35]
	v_lshlrev_b64 v[36:37], 13, v[36:37]
	v_lshlrev_b64 v[42:43], 13, v[42:43]
	v_lshlrev_b64 v[44:45], 13, v[44:45]
	v_lshlrev_b64 v[50:51], 11, v[50:51]
	v_lshl_add_u64 v[2:3], v[176:177], 0, v[2:3]
	v_lshl_add_u64 v[6:7], v[176:177], 0, v[4:5]
	v_lshl_add_u64 v[10:11], v[176:177], 0, v[10:11]
	v_lshl_add_u64 v[14:15], v[176:177], 0, v[12:13]
	v_lshl_add_u64 v[18:19], v[178:179], 0, v[18:19]
	v_lshl_add_u64 v[22:23], v[178:179], 0, v[20:21]
	v_lshl_add_u64 v[26:27], v[178:179], 0, v[26:27]
	v_lshl_add_u64 v[30:31], v[178:179], 0, v[28:29]
	v_lshl_add_u64 v[34:35], v[178:179], 0, v[34:35]
	v_lshl_add_u64 v[38:39], v[178:179], 0, v[36:37]
	v_lshl_add_u64 v[42:43], v[178:179], 0, v[42:43]
	v_lshl_add_u64 v[46:47], v[178:179], 0, v[44:45]
	v_lshl_add_u64 v[50:51], v[180:181], 0, v[50:51]
	global_load_dwordx4 v[2:5], v[2:3], off
	s_nop 0
	global_load_dwordx4 v[6:9], v[6:7], off
	s_nop 0
	global_load_dwordx4 v[10:13], v[10:11], off
	s_nop 0
	global_load_dwordx4 v[14:17], v[14:15], off
	s_nop 0
	global_load_dwordx4 v[18:21], v[18:19], off
	s_nop 0
	global_load_dwordx4 v[22:25], v[22:23], off
	s_nop 0
	global_load_dwordx4 v[26:29], v[26:27], off
	s_nop 0
	global_load_dwordx4 v[30:33], v[30:31], off
	s_nop 0
	global_load_dwordx4 v[34:37], v[34:35], off
	s_nop 0
	global_load_dwordx4 v[38:41], v[38:39], off
	s_nop 0
	global_load_dwordx4 v[42:45], v[42:43], off
	s_nop 0
	global_load_dwordx4 v[46:49], v[46:47], off
	s_lshl_b32 s77, s87, 0
	global_load_dwordx4 v[50:53], v[50:51], off
	s_add_i32 s77, s77, s36
	s_and_b32 s78, s77, 3
	s_cmp_lt_u32 s77, 4
	s_cbranch_scc1 .LBB0_488
	s_lshl_b32 s0, s78, 2
	s_add_i32 s0, s0, 0
	s_add_i32 s0, s0, 0x15010
	v_mov_b32_e32 v209, s0
	ds_read_b32 v209, v209
	s_and_b32 s1, s77, -4
	s_waitcnt lgkmcnt(0)
	v_cmp_le_u32_e32 vcc, s1, v209
	s_cbranch_vccnz .LBB0_487

.LBB0_495:
	s_add_i32 s1, s87, 3
	s_cmp_lt_u32 s1, s12
	s_cselect_b32 s1, s1, s86
	s_lshl_b32 s1, s1, 4
	s_add_i32 s1, s1, s13
	s_waitcnt vmcnt(0)
	v_add_u32_e32 v106, s1, v167
	v_ashrrev_i32_e32 v107, 31, v106
	v_add_u32_e32 v108, s1, v188
	v_lshlrev_b64 v[106:107], 12, v[106:107]
	v_ashrrev_i32_e32 v109, 31, v108
	v_lshl_add_u64 v[106:107], v[176:177], 0, v[106:107]
	v_lshlrev_b64 v[108:109], 12, v[108:109]
	v_lshl_add_u64 v[108:109], v[176:177], 0, v[108:109]
	global_load_dwordx4 v[142:145], v[106:107], off
	global_load_dwordx4 v[146:149], v[108:109], off
	v_add_u32_e32 v106, s1, v189
	v_ashrrev_i32_e32 v107, 31, v106
	v_add_u32_e32 v108, s1, v190
	v_lshlrev_b64 v[106:107], 12, v[106:107]
	v_ashrrev_i32_e32 v109, 31, v108
	v_lshl_add_u64 v[106:107], v[176:177], 0, v[106:107]
	v_lshlrev_b64 v[108:109], 12, v[108:109]
	v_lshl_add_u64 v[108:109], v[176:177], 0, v[108:109]
	global_load_dwordx4 v[150:153], v[106:107], off
	global_load_dwordx4 v[154:157], v[108:109], off
	v_add_u32_e32 v106, s1, v191
	v_ashrrev_i32_e32 v107, 31, v106
	v_add_u32_e32 v108, s1, v192
	v_lshlrev_b64 v[106:107], 13, v[106:107]
	v_ashrrev_i32_e32 v109, 31, v108
	v_lshl_add_u64 v[106:107], v[178:179], 0, v[106:107]
	v_lshlrev_b64 v[108:109], 13, v[108:109]
	v_lshl_add_u64 v[108:109], v[178:179], 0, v[108:109]
	global_load_dwordx4 v[110:113], v[106:107], off
	global_load_dwordx4 v[114:117], v[108:109], off
	v_add_u32_e32 v106, s1, v193
	v_ashrrev_i32_e32 v107, 31, v106
	v_add_u32_e32 v108, s1, v194
	v_lshlrev_b64 v[106:107], 13, v[106:107]
	v_ashrrev_i32_e32 v109, 31, v108
	v_lshl_add_u64 v[106:107], v[178:179], 0, v[106:107]
	v_lshlrev_b64 v[108:109], 13, v[108:109]
	v_lshl_add_u64 v[108:109], v[178:179], 0, v[108:109]
	global_load_dwordx4 v[118:121], v[106:107], off
	global_load_dwordx4 v[122:125], v[108:109], off
	v_add_u32_e32 v106, s1, v195
	v_ashrrev_i32_e32 v107, 31, v106
	v_add_u32_e32 v108, s1, v196
	v_lshlrev_b64 v[106:107], 13, v[106:107]
	v_ashrrev_i32_e32 v109, 31, v108
	v_lshl_add_u64 v[106:107], v[178:179], 0, v[106:107]
	v_lshlrev_b64 v[108:109], 13, v[108:109]
	v_lshl_add_u64 v[108:109], v[178:179], 0, v[108:109]
	global_load_dwordx4 v[126:129], v[106:107], off
	global_load_dwordx4 v[130:133], v[108:109], off
	v_add_u32_e32 v106, s1, v197
	v_ashrrev_i32_e32 v107, 31, v106
	v_add_u32_e32 v108, s1, v198
	v_lshlrev_b64 v[106:107], 13, v[106:107]
	v_ashrrev_i32_e32 v109, 31, v108
	v_lshl_add_u64 v[106:107], v[178:179], 0, v[106:107]
	v_lshlrev_b64 v[108:109], 13, v[108:109]
	v_lshl_add_u64 v[108:109], v[178:179], 0, v[108:109]
	global_load_dwordx4 v[134:137], v[106:107], off
	global_load_dwordx4 v[138:141], v[108:109], off
	v_add_u32_e32 v106, s1, v171
	v_ashrrev_i32_e32 v107, 31, v106
	v_lshlrev_b64 v[106:107], 11, v[106:107]
	v_lshl_add_u64 v[106:107], v[180:181], 0, v[106:107]
	global_load_dwordx4 v[106:109], v[106:107], off
	s_lshl_b32 s77, s0, 0
	s_add_i32 s77, s77, s36
	s_and_b32 s78, s77, 3
	s_cmp_lt_u32 s77, 4
	s_cbranch_scc1 .LBB0_499
	s_lshl_b32 s0, s78, 2
	s_add_i32 s0, s0, 0
	s_add_i32 s0, s0, 0x15010
	v_mov_b32_e32 v209, s0
	ds_read_b32 v209, v209
	s_and_b32 s1, s77, -4
	s_waitcnt lgkmcnt(0)
	v_cmp_le_u32_e32 vcc, s1, v209
	s_cbranch_vccnz .LBB0_498

.LBB0_504:
	s_add_i32 s1, s87, 4
	s_cmp_lt_u32 s1, s12
	s_cselect_b32 s1, s1, s86
	s_lshl_b32 s1, s1, 4
	s_add_i32 s1, s1, s13
	s_waitcnt vmcnt(7)
	v_add_u32_e32 v54, s1, v167
	v_add_u32_e32 v56, s1, v188
	v_ashrrev_i32_e32 v55, 31, v54
	v_ashrrev_i32_e32 v57, 31, v56
	v_lshlrev_b64 v[54:55], 12, v[54:55]
	v_lshlrev_b64 v[56:57], 12, v[56:57]
	v_lshl_add_u64 v[54:55], v[176:177], 0, v[54:55]
	v_lshl_add_u64 v[56:57], v[176:177], 0, v[56:57]
	global_load_dwordx4 v[102:105], v[54:55], off
	global_load_dwordx4 v[70:73], v[56:57], off
	v_add_u32_e32 v54, s1, v189
	v_add_u32_e32 v56, s1, v190
	v_ashrrev_i32_e32 v55, 31, v54
	v_ashrrev_i32_e32 v57, 31, v56
	v_lshlrev_b64 v[54:55], 12, v[54:55]
	v_lshlrev_b64 v[56:57], 12, v[56:57]
	v_lshl_add_u64 v[54:55], v[176:177], 0, v[54:55]
	v_lshl_add_u64 v[56:57], v[176:177], 0, v[56:57]
	global_load_dwordx4 v[98:101], v[54:55], off
	global_load_dwordx4 v[74:77], v[56:57], off
	v_add_u32_e32 v54, s1, v191
	v_add_u32_e32 v56, s1, v192
	s_waitcnt vmcnt(9)
	v_add_u32_e32 v58, s1, v193
	v_add_u32_e32 v60, s1, v194
	s_waitcnt vmcnt(7)
	v_add_u32_e32 v62, s1, v195
	v_add_u32_e32 v64, s1, v196
	s_waitcnt vmcnt(5)
	v_add_u32_e32 v66, s1, v197
	v_add_u32_e32 v68, s1, v198
	s_waitcnt vmcnt(4)
	v_add_u32_e32 v78, s1, v171
	v_ashrrev_i32_e32 v55, 31, v54
	v_ashrrev_i32_e32 v57, 31, v56
	v_ashrrev_i32_e32 v59, 31, v58
	v_ashrrev_i32_e32 v61, 31, v60
	v_ashrrev_i32_e32 v63, 31, v62
	v_ashrrev_i32_e32 v65, 31, v64
	v_ashrrev_i32_e32 v67, 31, v66
	v_ashrrev_i32_e32 v69, 31, v68
	v_ashrrev_i32_e32 v79, 31, v78
	v_lshlrev_b64 v[54:55], 13, v[54:55]
	v_lshlrev_b64 v[56:57], 13, v[56:57]
	v_lshlrev_b64 v[58:59], 13, v[58:59]
	v_lshlrev_b64 v[60:61], 13, v[60:61]
	v_lshlrev_b64 v[62:63], 13, v[62:63]
	v_lshlrev_b64 v[64:65], 13, v[64:65]
	v_lshlrev_b64 v[66:67], 13, v[66:67]
	v_lshlrev_b64 v[68:69], 13, v[68:69]
	v_lshlrev_b64 v[78:79], 11, v[78:79]
	v_lshl_add_u64 v[54:55], v[178:179], 0, v[54:55]
	v_lshl_add_u64 v[56:57], v[178:179], 0, v[56:57]
	v_lshl_add_u64 v[58:59], v[178:179], 0, v[58:59]
	v_lshl_add_u64 v[60:61], v[178:179], 0, v[60:61]
	v_lshl_add_u64 v[62:63], v[178:179], 0, v[62:63]
	v_lshl_add_u64 v[64:65], v[178:179], 0, v[64:65]
	v_lshl_add_u64 v[66:67], v[178:179], 0, v[66:67]
	v_lshl_add_u64 v[68:69], v[178:179], 0, v[68:69]
	v_lshl_add_u64 v[78:79], v[180:181], 0, v[78:79]
	global_load_dwordx4 v[82:85], v[54:55], off
	s_nop 0
	global_load_dwordx4 v[54:57], v[56:57], off
	s_nop 0
	global_load_dwordx4 v[86:89], v[58:59], off
	s_nop 0
	global_load_dwordx4 v[58:61], v[60:61], off
	s_nop 0
	global_load_dwordx4 v[90:93], v[62:63], off
	s_nop 0
	global_load_dwordx4 v[62:65], v[64:65], off
	s_nop 0
	global_load_dwordx4 v[94:97], v[66:67], off
	s_nop 0
	global_load_dwordx4 v[66:69], v[68:69], off
	s_lshl_b32 s77, s0, 0
	global_load_dwordx4 v[78:81], v[78:79], off
	s_add_i32 s77, s77, s36
	s_and_b32 s78, s77, 3
	s_cmp_lt_u32 s77, 4
	s_cbranch_scc1 .LBB0_508
	s_lshl_b32 s0, s78, 2
	s_add_i32 s0, s0, 0
	s_add_i32 s0, s0, 0x15010
	v_mov_b32_e32 v209, s0
	ds_read_b32 v209, v209
	s_and_b32 s1, s77, -4
	s_waitcnt lgkmcnt(0)
	v_cmp_le_u32_e32 vcc, s1, v209
	s_cbranch_vccnz .LBB0_507

.LBB0_518:
.LBB0_519:
	s_setprio 0
	s_cmp_lg_u32 s82, 5
	s_cbranch_scc1 .Le_not5
	v_mov_b32_e32 v2, 0x15020
	s_mov_b64 s[0:1], exec
	s_mov_b64 exec, 1
	ds_add_u32 v2, v203
	s_mov_b64 exec, s[0:1]
.Le_not5:
	s_cmp_lt_u32 s82, 6
	s_cbranch_scc1 .Ldc4_skip
	s_branch .Ldc4_entry

.Ldc4_skip:
	s_cmp_eq_u32 s82, 4
	s_cbranch_scc1 .LBB0_552
	s_mul_i32 s0, s82, 0x410
	s_add_i32 s48, s0, 0
	s_add_i32 s48, s48, 0x15040
	s_cmp_gt_i32 s82, 5
	v_readlane_b32 s0, v254, 39
	s_mulk_i32 s82, 0x4800
	s_cselect_b32 s0, s0, 0
	s_waitcnt vmcnt(12)
	v_lshrrev_b32_e32 v2, 5, v161
	v_and_b32_e32 v0, 7, v166
	s_add_i32 s0, s0, s82
	s_cmp_eq_u32 s82, 0x16800
	s_cselect_b32 s0, 0x20800, s0
	s_waitcnt vmcnt(1)
	v_and_b32_e32 v147, 31, v166
	v_lshrrev_b32_e32 v149, 3, v161
	v_lshlrev_b32_e32 v148, 3, v0
	v_lshlrev_b32_e32 v0, 4, v0
	v_or_b32_e32 v5, 32, v161
	v_lshlrev_b32_e32 v150, 2, v2
	s_getreg_b32 s49, hwreg(HW_REG_XCC_ID, 0, 4)
	v_lshlrev_b32_e32 v146, 3, v2
	v_add_u32_e32 v3, s0, v0
	v_mul_u32_u24_e32 v4, 0x90, v149
	v_mul_u32_u24_e32 v225, 0x90, v5
	v_and_b32_e32 v226, 15, v166
	v_mov_b32_e32 v5, 0x4000
	v_lshl_or_b32 v233, v147, 9, v150
	s_mov_b32 s50, 0
	v_cmp_eq_u32_e64 s[38:39], 0, v161
	v_lshl_add_u32 v151, v2, 4, s0
	v_add_u32_e32 v167, s0, v146
	v_mul_u32_u24_e32 v224, 0x90, v147
	v_cmp_gt_u32_e64 s[0:1], 16, v147
	v_lshl_or_b32 v227, v161, 9, v5
	v_lshl_add_u64 v[152:153], s[6:7], 0, v[0:1]
	v_or_b32_e32 v228, 0xffffffc0, v161
	v_lshl_add_u32 v229, v161, 2, s48
	v_mad_i32_i24 v230, v2, -4, v147
	v_sub_u32_e32 v231, v226, v150
	v_or_b32_e32 v232, 59, v150
	v_or_b32_e32 v234, 48, v233
	v_or_b32_e32 v235, 32, v233
	v_or_b32_e32 v236, 16, v233
	v_lshl_or_b32 v237, v147, 10, v146
	v_add_u32_e32 v238, v3, v4
	s_mov_b32 s51, s49
	s_mov_b32 s76, s18
	s_branch .LBB0_522

	.amdhsa_kernel _Z4mega6Params
		.amdhsa_group_segment_fixed_size 18432
		.amdhsa_private_segment_fixed_size 0
		.amdhsa_kernarg_size 544
		.amdhsa_user_sgpr_count 2
		.amdhsa_user_sgpr_dispatch_ptr 0
		.amdhsa_user_sgpr_queue_ptr 0
		.amdhsa_user_sgpr_kernarg_segment_ptr 1
		.amdhsa_user_sgpr_dispatch_id 0
		.amdhsa_user_sgpr_kernarg_preload_length 0
		.amdhsa_user_sgpr_kernarg_preload_offset 0
		.amdhsa_user_sgpr_private_segment_size 0
		.amdhsa_uses_dynamic_stack 0
		.amdhsa_enable_private_segment 0
		.amdhsa_system_sgpr_workgroup_id_x 1
		.amdhsa_system_sgpr_workgroup_id_y 0
		.amdhsa_system_sgpr_workgroup_id_z 0
		.amdhsa_system_sgpr_workgroup_info 0
		.amdhsa_system_vgpr_workitem_id 2
		.amdhsa_next_free_vgpr 256
		.amdhsa_next_free_sgpr 100
		.amdhsa_accum_offset 256
		.amdhsa_reserve_vcc 1
		.amdhsa_float_round_mode_32 0
		.amdhsa_float_round_mode_16_64 0
		.amdhsa_float_denorm_mode_32 3
		.amdhsa_float_denorm_mode_16_64 3
		.amdhsa_dx10_clamp 1
		.amdhsa_ieee_mode 1
		.amdhsa_fp16_overflow 0
		.amdhsa_tg_split 0
		.amdhsa_exception_fp_ieee_invalid_op 0
		.amdhsa_exception_fp_denorm_src 0
		.amdhsa_exception_fp_ieee_div_zero 0
		.amdhsa_exception_fp_ieee_overflow 0
		.amdhsa_exception_fp_ieee_underflow 0
		.amdhsa_exception_fp_ieee_inexact 0
		.amdhsa_exception_int_div_zero 0
	.end_amdhsa_kernel

amdhsa.kernels:
  - .agpr_count:     0
    .args:
      - .offset:         0
        .size:           288
        .value_kind:     by_value
      - .offset:         288
        .size:           4
        .value_kind:     hidden_block_count_x
      - .offset:         292
        .size:           4
        .value_kind:     hidden_block_count_y
      - .offset:         296
        .size:           4
        .value_kind:     hidden_block_count_z
      - .offset:         300
        .size:           2
        .value_kind:     hidden_group_size_x
      - .offset:         302
        .size:           2
        .value_kind:     hidden_group_size_y
      - .offset:         304
        .size:           2
        .value_kind:     hidden_group_size_z
      - .offset:         306
        .size:           2
        .value_kind:     hidden_remainder_x
      - .offset:         308
        .size:           2
        .value_kind:     hidden_remainder_y
      - .offset:         310
        .size:           2
        .value_kind:     hidden_remainder_z
      - .offset:         328
        .size:           8
        .value_kind:     hidden_global_offset_x
      - .offset:         336
        .size:           8
        .value_kind:     hidden_global_offset_y
      - .offset:         344
        .size:           8
        .value_kind:     hidden_global_offset_z
      - .offset:         352
        .size:           2
        .value_kind:     hidden_grid_dims
      - .offset:         376
        .size:           8
        .value_kind:     hidden_multigrid_sync_arg
      - .offset:         408
        .size:           4
        .value_kind:     hidden_dynamic_lds_size
    .group_segment_fixed_size: 18432
    .kernarg_segment_align: 8
    .kernarg_segment_size: 544
    .language:       OpenCL C
    .language_version:
      - 2
      - 0
    .max_flat_workgroup_size: 512
    .name:           _Z4mega6Params
    .private_segment_fixed_size: 0
    .sgpr_count:     106
    .sgpr_spill_count: 376
    .symbol:         _Z4mega6Params.kd
    .uniform_work_group_size: 1
    .uses_dynamic_stack: false
    .vgpr_count:     256
    .vgpr_spill_count: 0
    .wavefront_size: 64
